# parked stores: the v_cvt_pk write the parking registers directly (no v_mov copies); on top of v77
# baseline (speedup 1.0000x reference)
; __device__ __forceinline__ float sum_x16(float v) { float a, b; swap16(v, a, b); return a + b; }
; __device__ __forceinline__ float sum_x32(float v) { float a, b; swap32(v, a, b); return a + b; }
; __device__ __forceinline__ void st16_wt(void* p, u32x4 v) { if (WT_STORES) asm volatile("global_store_dwordx4 %0, %1, off sc1\n\ts_nop 1" :: "v"(p), "v"(v) : "memory"); else *(u32x4*)p = v; }
; __device__ __forceinline__ unsigned cvt_pk_bf16(float lo, float hi) { unsigned r; asm volatile("v_cvt_pk_bf16_f32 %0, %1, %2" : "=v"(r) : "v"(lo), "v"(hi)); return r; }
;     __device__ __forceinline__ void operator()(const f32x4 (&acc)[2][2][4][2], const Unit& u, int wr, int wc, int fr, int fq, const bool reuse, PG8_LAS float* rscr, PG8_LAS const float* gains) const {
;     ...
;                 if (type < 2) {
;                     float ss = 0.f;
; #pragma unroll
;                     for (int bj = 0; bj < 2; ++bj)
; #pragma unroll
;                         for (int n = 0; n < 2; ++n) { const f32x4 x = v[bj][n]; ss += (x[0] * x[0] + x[1] * x[1]) + (x[2] * x[2] + x[3] * x[3]); }
;                     ss = sum_x16(ss); ss = sum_x32(ss);
;                     const float inv = __builtin_amdgcn_rsqf(ss * (1.0f / 64.0f) + RMS_EPS);
; #pragma unroll
;                     for (int bj = 0; bj < 2; ++bj)
; #pragma unroll
;                         for (int n = 0; n < 2; ++n) v[bj][n] = v[bj][n] * gv[bj][n] * inv;
;                 }
;                 bf16_t* p = p0 + (size_t)(8 * ai + m) * step16;
; #pragma unroll
;                 for (int bj = 0; bj < 2; ++bj) { u32x4 w; w.x = cvt_pk_bf16(v[bj][0][0], v[bj][0][1]); w.y = cvt_pk_bf16(v[bj][0][2], v[bj][0][3]); w.z = cvt_pk_bf16(v[bj][1][0], v[bj][1][1]); w.w = cvt_pk_bf16(v[bj][1][2], v[bj][1][3]);
;                     st16_wt(p + 32 * bj, w); }
.LBB0_240:
	s_nop 0
	v_mad_u64_u32 v[80:81], s[12:13], s72, 10, v[96:97]
	v_mov_b32_e32 v254, v80
	v_mov_b32_e32 v255, v81
	s_and_b64 vcc, exec, s[38:39]
	v_cvt_pk_bf16_f32 v244, v68, v69
	v_cvt_pk_bf16_f32 v245, v70, v71
	v_cvt_pk_bf16_f32 v246, v64, v65
	v_cvt_pk_bf16_f32 v247, v66, v67
	v_cvt_pk_bf16_f32 v248, v76, v77
	v_cvt_pk_bf16_f32 v249, v78, v79
	v_cvt_pk_bf16_f32 v250, v72, v73
	v_cvt_pk_bf16_f32 v251, v74, v75
	s_cbranch_vccnz .LBB0_242
	s_nop 0
	v_pk_mul_f32 v[64:65], v[48:49], v[48:49]
	v_pk_fma_f32 v[64:65], v[50:51], v[50:51], v[64:65]
	v_pk_fma_f32 v[64:65], v[52:53], v[52:53], v[64:65]
	v_pk_fma_f32 v[64:65], v[54:55], v[54:55], v[64:65]
	v_pk_fma_f32 v[64:65], v[56:57], v[56:57], v[64:65]
	v_pk_fma_f32 v[64:65], v[58:59], v[58:59], v[64:65]
	v_pk_fma_f32 v[64:65], v[60:61], v[60:61], v[64:65]
	v_pk_fma_f32 v[64:65], v[62:63], v[62:63], v[64:65]
	v_add_f32_e32 v64, v64, v65
	v_mov_b32_e32 v65, v64
	s_nop 1
	v_permlane16_swap_b32_e32 v64, v65
	v_add_f32_e32 v64, v64, v65
	v_mov_b32_e32 v65, v64
	s_nop 1
	v_permlane32_swap_b32_e32 v64, v65
	v_add_f32_e32 v64, v64, v65
	v_fmamk_f32 v64, v64, 0x3c800000, v190
	v_rsq_f32_e32 v64, v64
	s_waitcnt lgkmcnt(0)
	v_pk_mul_f32 v[54:55], v[54:55], v[158:159]
	v_pk_mul_f32 v[52:53], v[52:53], v[156:157]
	v_pk_mul_f32 v[50:51], v[50:51], v[154:155]
	v_pk_mul_f32 v[48:49], v[48:49], v[152:153]
	v_pk_mul_f32 v[62:63], v[62:63], v[150:151]
	v_pk_mul_f32 v[60:61], v[60:61], v[148:149]
	v_pk_mul_f32 v[58:59], v[58:59], v[146:147]
	v_pk_mul_f32 v[56:57], v[56:57], v[144:145]
	v_pk_mul_f32 v[54:55], v[54:55], v[64:65] op_sel_hi:[1,0]
	v_pk_mul_f32 v[52:53], v[52:53], v[64:65] op_sel_hi:[1,0]
	v_pk_mul_f32 v[50:51], v[50:51], v[64:65] op_sel_hi:[1,0]
	v_pk_mul_f32 v[48:49], v[48:49], v[64:65] op_sel_hi:[1,0]
	v_pk_mul_f32 v[62:63], v[62:63], v[64:65] op_sel_hi:[1,0]
	v_pk_mul_f32 v[60:61], v[60:61], v[64:65] op_sel_hi:[1,0]
	v_pk_mul_f32 v[58:59], v[58:59], v[64:65] op_sel_hi:[1,0]
	v_pk_mul_f32 v[56:57], v[56:57], v[64:65] op_sel_hi:[1,0]
.LBB0_242:
	s_nop 0
	v_lshl_add_u64 v[64:65], v[80:81], 0, s[88:89]
	s_and_b64 vcc, exec, s[38:39]
	v_cvt_pk_bf16_f32 v214, v52, v53
	v_cvt_pk_bf16_f32 v215, v54, v55
	v_cvt_pk_bf16_f32 v216, v48, v49
	v_cvt_pk_bf16_f32 v217, v50, v51
	v_cvt_pk_bf16_f32 v218, v60, v61
	v_cvt_pk_bf16_f32 v219, v62, v63
	v_cvt_pk_bf16_f32 v220, v56, v57
	v_cvt_pk_bf16_f32 v221, v58, v59
	s_cbranch_vccnz .LBB0_244
	s_nop 0
	v_pk_mul_f32 v[48:49], v[32:33], v[32:33]
	v_pk_fma_f32 v[48:49], v[34:35], v[34:35], v[48:49]
	v_pk_fma_f32 v[48:49], v[36:37], v[36:37], v[48:49]
	v_pk_fma_f32 v[48:49], v[38:39], v[38:39], v[48:49]
	v_pk_fma_f32 v[48:49], v[40:41], v[40:41], v[48:49]
	v_pk_fma_f32 v[48:49], v[42:43], v[42:43], v[48:49]
	v_pk_fma_f32 v[48:49], v[44:45], v[44:45], v[48:49]
	v_pk_fma_f32 v[48:49], v[46:47], v[46:47], v[48:49]
	v_add_f32_e32 v48, v48, v49
	v_mov_b32_e32 v49, v48
	s_nop 1
	v_permlane16_swap_b32_e32 v48, v49
	v_add_f32_e32 v48, v48, v49
	v_mov_b32_e32 v49, v48
	s_nop 1
	v_permlane32_swap_b32_e32 v48, v49
	v_add_f32_e32 v48, v48, v49
	v_fmamk_f32 v48, v48, 0x3c800000, v190
	v_rsq_f32_e32 v48, v48
	s_waitcnt lgkmcnt(0)
	v_pk_mul_f32 v[38:39], v[38:39], v[158:159]
	v_pk_mul_f32 v[36:37], v[36:37], v[156:157]
	v_pk_mul_f32 v[34:35], v[34:35], v[154:155]
	v_pk_mul_f32 v[32:33], v[32:33], v[152:153]
	v_pk_mul_f32 v[46:47], v[46:47], v[150:151]
	v_pk_mul_f32 v[44:45], v[44:45], v[148:149]
	v_pk_mul_f32 v[42:43], v[42:43], v[146:147]
	v_pk_mul_f32 v[40:41], v[40:41], v[144:145]
	v_pk_mul_f32 v[38:39], v[38:39], v[48:49] op_sel_hi:[1,0]
	v_pk_mul_f32 v[36:37], v[36:37], v[48:49] op_sel_hi:[1,0]
	v_pk_mul_f32 v[34:35], v[34:35], v[48:49] op_sel_hi:[1,0]
	v_pk_mul_f32 v[32:33], v[32:33], v[48:49] op_sel_hi:[1,0]
	v_pk_mul_f32 v[46:47], v[46:47], v[48:49] op_sel_hi:[1,0]
	v_pk_mul_f32 v[44:45], v[44:45], v[48:49] op_sel_hi:[1,0]
	v_pk_mul_f32 v[42:43], v[42:43], v[48:49] op_sel_hi:[1,0]
	v_pk_mul_f32 v[40:41], v[40:41], v[48:49] op_sel_hi:[1,0]
;     __device__ __forceinline__ void side_finish(const Side& s, int lane) const {
;         if (MODE == 0 && s.row < xrows) {
;             float q = 0.f;
; #pragma unroll
;             for (int j = 0; j < 4; ++j) q += (s.v[j][0] * s.v[j][0] + s.v[j][1] * s.v[j][1]) + (s.v[j][2] * s.v[j][2] + s.v[j][3] * s.v[j][3]);
;             const float rstd = __builtin_amdgcn_rsqf(wave_sum(q) * (1.0f / 1024.0f) + 1e-6f);
;             const bool odd = lane & 1;
;             bf16_t* orow = xd + (size_t)s.row * 1024 + 4 * (lane & ~1);
; #pragma unroll
;             for (int jp = 0; jp < 2; ++jp) {
;                 const int ja = 2 * jp, jb = 2 * jp + 1;
;                 const unsigned pax = cvt_pk_bf16(s.v[ja][0] * rstd, s.v[ja][1] * rstd), pay = cvt_pk_bf16(s.v[ja][2] * rstd, s.v[ja][3] * rstd);
;                 const unsigned pbx = cvt_pk_bf16(s.v[jb][0] * rstd, s.v[jb][1] * rstd), pby = cvt_pk_bf16(s.v[jb][2] * rstd, s.v[jb][3] * rstd);
;                 const unsigned rx = (unsigned)__builtin_amdgcn_update_dpp(0, (int)(odd ? pax : pbx), 0xB1, 0xF, 0xF, true), ry = (unsigned)__builtin_amdgcn_update_dpp(0, (int)(odd ? pay : pby), 0xB1, 0xF, 0xF, true);
;     __device__ __forceinline__ void operator()(const f32x4 (&acc)[2][2][4][2], const Unit& u, int wr, int wc, int fr, int fq, const bool reuse, PG8_LAS float* rscr, PG8_LAS const float* gains) const {
;     ...
;                 if (type < 2) {
;                     float ss = 0.f;
; #pragma unroll
;                     for (int bj = 0; bj < 2; ++bj)
; #pragma unroll
;                         for (int n = 0; n < 2; ++n) { const f32x4 x = v[bj][n]; ss += (x[0] * x[0] + x[1] * x[1]) + (x[2] * x[2] + x[3] * x[3]); }
;                     ss = sum_x16(ss); ss = sum_x32(ss);
;                     const float inv = __builtin_amdgcn_rsqf(ss * (1.0f / 64.0f) + RMS_EPS);
; #pragma unroll
;                     for (int bj = 0; bj < 2; ++bj)
; #pragma unroll
;                         for (int n = 0; n < 2; ++n) v[bj][n] = v[bj][n] * gv[bj][n] * inv;
;                 }
;                 bf16_t* p = p0 + (size_t)(8 * ai + m) * step16;
; #pragma unroll
;                 for (int bj = 0; bj < 2; ++bj) { u32x4 w; w.x = cvt_pk_bf16(v[bj][0][0], v[bj][0][1]); w.y = cvt_pk_bf16(v[bj][0][2], v[bj][0][3]); w.z = cvt_pk_bf16(v[bj][1][0], v[bj][1][1]); w.w = cvt_pk_bf16(v[bj][1][2], v[bj][1][3]);
;                     st16_wt(p + 32 * bj, w); }
.LBB0_244:
	s_nop 0
	v_lshl_add_u64 v[48:49], v[64:65], 0, s[88:89]
	s_and_b64 vcc, exec, s[38:39]
	v_cvt_pk_bf16_f32 v0, v36, v37
	v_cvt_pk_bf16_f32 v1, v38, v39
	v_cvt_pk_bf16_f32 v2, v32, v33
	v_cvt_pk_bf16_f32 v3, v34, v35
	v_cvt_pk_bf16_f32 v4, v44, v45
	v_cvt_pk_bf16_f32 v5, v46, v47
	v_cvt_pk_bf16_f32 v6, v40, v41
	v_cvt_pk_bf16_f32 v7, v42, v43
	s_cbranch_vccnz .LBB0_246
	s_nop 0
	v_pk_mul_f32 v[32:33], v[16:17], v[16:17]
	v_pk_fma_f32 v[32:33], v[18:19], v[18:19], v[32:33]
	v_pk_fma_f32 v[32:33], v[20:21], v[20:21], v[32:33]
	v_pk_fma_f32 v[32:33], v[22:23], v[22:23], v[32:33]
	v_pk_fma_f32 v[32:33], v[24:25], v[24:25], v[32:33]
	v_pk_fma_f32 v[32:33], v[26:27], v[26:27], v[32:33]
	v_pk_fma_f32 v[32:33], v[28:29], v[28:29], v[32:33]
	v_pk_fma_f32 v[32:33], v[30:31], v[30:31], v[32:33]
	v_add_f32_e32 v32, v32, v33
	v_mov_b32_e32 v33, v32
	s_nop 1
	v_permlane16_swap_b32_e32 v32, v33
	v_add_f32_e32 v32, v32, v33
	v_mov_b32_e32 v33, v32
	s_nop 1
	v_permlane32_swap_b32_e32 v32, v33
	v_add_f32_e32 v32, v32, v33
	v_fmamk_f32 v32, v32, 0x3c800000, v190
	v_rsq_f32_e32 v32, v32
	s_waitcnt lgkmcnt(0)
	v_pk_mul_f32 v[22:23], v[22:23], v[158:159]
	v_pk_mul_f32 v[20:21], v[20:21], v[156:157]
	v_pk_mul_f32 v[18:19], v[18:19], v[154:155]
	v_pk_mul_f32 v[16:17], v[16:17], v[152:153]
	v_pk_mul_f32 v[26:27], v[26:27], v[150:151]
	v_pk_mul_f32 v[24:25], v[24:25], v[148:149]
	v_pk_mul_f32 v[30:31], v[30:31], v[146:147]
	v_pk_mul_f32 v[28:29], v[28:29], v[144:145]
	v_pk_mul_f32 v[22:23], v[22:23], v[32:33] op_sel_hi:[1,0]
	v_pk_mul_f32 v[20:21], v[20:21], v[32:33] op_sel_hi:[1,0]
	v_pk_mul_f32 v[18:19], v[18:19], v[32:33] op_sel_hi:[1,0]
	v_pk_mul_f32 v[16:17], v[16:17], v[32:33] op_sel_hi:[1,0]
	v_pk_mul_f32 v[26:27], v[26:27], v[32:33] op_sel_hi:[1,0]
	v_pk_mul_f32 v[24:25], v[24:25], v[32:33] op_sel_hi:[1,0]
	v_pk_mul_f32 v[30:31], v[30:31], v[32:33] op_sel_hi:[1,0]
	v_pk_mul_f32 v[28:29], v[28:29], v[32:33] op_sel_hi:[1,0]
.LBB0_246:
	s_nop 0
	v_lshl_add_u64 v[32:33], v[48:49], 0, s[88:89]
	s_andn2_b64 vcc, exec, s[80:81]
	v_cvt_pk_bf16_f32 v8, v20, v21
	v_cvt_pk_bf16_f32 v9, v22, v23
	v_cvt_pk_bf16_f32 v10, v16, v17
	v_cvt_pk_bf16_f32 v11, v18, v19
	v_cvt_pk_bf16_f32 v12, v24, v25
	v_cvt_pk_bf16_f32 v13, v26, v27
	v_cvt_pk_bf16_f32 v14, v28, v29
	v_cvt_pk_bf16_f32 v15, v30, v31
	s_mov_b32 s101, 8
	s_cbranch_vccnz .LBB0_248
	s_waitcnt vmcnt(8)
	v_mul_f32_e32 v16, v211, v211
	v_mul_f32_e32 v17, v213, v213
	v_fmac_f32_e32 v16, v210, v210
	v_fmac_f32_e32 v17, v212, v212
	v_add_f32_e32 v16, v16, v17
	v_mul_f32_e32 v17, v207, v207
	v_mul_f32_e32 v18, v209, v209
	v_fmac_f32_e32 v17, v206, v206
	v_fmac_f32_e32 v18, v208, v208
	v_add_f32_e32 v17, v17, v18
	v_add_f32_e32 v16, v17, v16
	v_mul_f32_e32 v17, v203, v203
	v_mul_f32_e32 v18, v205, v205
	v_fmac_f32_e32 v17, v202, v202
	v_fmac_f32_e32 v18, v204, v204
	v_add_f32_e32 v17, v17, v18
	v_add_f32_e32 v16, v17, v16
	v_mul_f32_e32 v17, v199, v199
	v_mul_f32_e32 v18, v201, v201
	v_fmac_f32_e32 v17, v198, v198
	v_fmac_f32_e32 v18, v200, v200
	v_add_f32_e32 v17, v17, v18
	v_add_f32_e32 v16, v17, v16
	s_ashr_i32 s77, s76, 31
	s_lshl_b64 s[12:13], s[76:77], 11
	v_add_f32_dpp v16, v16, v16 quad_perm:[1,0,3,2] row_mask:0xf bank_mask:0xf bound_ctrl:1
	v_lshl_add_u64 v[20:21], v[176:177], 0, s[12:13]
	v_mov_b32_e32 v183, v161
	v_add_f32_dpp v16, v16, v16 quad_perm:[2,3,0,1] row_mask:0xf bank_mask:0xf bound_ctrl:1
	v_mov_b32_e32 v185, v161
	s_nop 0
	v_add_f32_dpp v16, v16, v16 row_half_mirror row_mask:0xf bank_mask:0xf bound_ctrl:1
	s_nop 1
	v_add_f32_dpp v16, v16, v16 row_mirror row_mask:0xf bank_mask:0xf bound_ctrl:1
	v_mov_b32_e32 v17, v16
	s_nop 1
	v_permlane16_swap_b32_e32 v16, v17
	v_add_f32_e32 v16, v16, v17
	v_mov_b32_e32 v17, v16
	s_nop 1
	v_permlane32_swap_b32_e32 v16, v17
	v_add_f32_e32 v16, v16, v17
	v_fmamk_f32 v16, v16, 0x3a800000, v190
	v_rsq_f32_e32 v24, v16
	s_nop 0
	v_mul_f32_e32 v16, v210, v24
	v_mul_f32_e32 v17, v211, v24
	v_cvt_pk_bf16_f32 v16, v16, v17
	v_mul_f32_e32 v17, v212, v24
	v_mul_f32_e32 v18, v213, v24
	v_cvt_pk_bf16_f32 v17, v17, v18
	v_mul_f32_e32 v18, v206, v24
	v_mul_f32_e32 v19, v207, v24
	v_cvt_pk_bf16_f32 v18, v18, v19
	v_mul_f32_e32 v19, v208, v24
	v_mul_f32_e32 v22, v209, v24
	v_cvt_pk_bf16_f32 v19, v19, v22
	v_cndmask_b32_e64 v22, v16, v18, s[34:35]
	v_cndmask_b32_e64 v23, v17, v19, s[34:35]
	s_nop 0
	v_mov_b32_dpp v22, v22 quad_perm:[1,0,3,2] row_mask:0xf bank_mask:0xf bound_ctrl:1
	v_mov_b32_dpp v23, v23 quad_perm:[1,0,3,2] row_mask:0xf bank_mask:0xf bound_ctrl:1
	v_cndmask_b32_e64 v16, v22, v16, s[34:35]
	v_cndmask_b32_e64 v17, v23, v17, s[34:35]
	v_cndmask_b32_e64 v18, v18, v22, s[34:35]
	v_cndmask_b32_e64 v19, v19, v23, s[34:35]
	v_lshl_add_u64 v[22:23], v[20:21], 0, v[182:183]
	global_store_dwordx4 v[22:23], v[16:19], off
	v_mul_f32_e32 v22, v201, v24
	v_lshl_add_u64 v[20:21], v[20:21], 0, v[184:185]
	v_mul_f32_e32 v16, v202, v24
	v_mul_f32_e32 v17, v203, v24
	v_cvt_pk_bf16_f32 v16, v16, v17
	v_mul_f32_e32 v17, v204, v24
	v_mul_f32_e32 v18, v205, v24
	v_cvt_pk_bf16_f32 v17, v17, v18
	v_mul_f32_e32 v18, v198, v24
	v_mul_f32_e32 v19, v199, v24
	v_cvt_pk_bf16_f32 v18, v18, v19
	v_mul_f32_e32 v19, v200, v24
	v_cvt_pk_bf16_f32 v19, v19, v22
	v_cndmask_b32_e64 v22, v16, v18, s[34:35]
	v_cndmask_b32_e64 v23, v17, v19, s[34:35]
	s_nop 0
	v_mov_b32_dpp v22, v22 quad_perm:[1,0,3,2] row_mask:0xf bank_mask:0xf bound_ctrl:1
	v_mov_b32_dpp v23, v23 quad_perm:[1,0,3,2] row_mask:0xf bank_mask:0xf bound_ctrl:1
	v_cndmask_b32_e64 v16, v22, v16, s[34:35]
	v_cndmask_b32_e64 v17, v23, v17, s[34:35]
	v_cndmask_b32_e64 v18, v18, v22, s[34:35]
	v_cndmask_b32_e64 v19, v19, v23, s[34:35]
	global_store_dwordx4 v[20:21], v[16:19], off

; __device__ __forceinline__ float sum_x16(float v) { float a, b; swap16(v, a, b); return a + b; }
; __device__ __forceinline__ float sum_x32(float v) { float a, b; swap32(v, a, b); return a + b; }
; __device__ __forceinline__ void st16_wt(void* p, u32x4 v) { if (WT_STORES) asm volatile("global_store_dwordx4 %0, %1, off sc1\n\ts_nop 1" :: "v"(p), "v"(v) : "memory"); else *(u32x4*)p = v; }
;     __device__ __forceinline__ void operator()(const f32x4 (&acc)[2][2][4][2], const Unit& u, int wr, int wc, int fr, int fq, const bool reuse, PG8_LAS float* rscr, PG8_LAS const float* gains) const {
;     ...
; #pragma unroll
;         for (int ai = 0; ai < 2; ++ai)
; #pragma unroll
;             for (int m = 0; m < 4; ++m) {
;                 const int r = u.pm * BM + ai * HALF + wr * 64 + m * 16 + fr;
;                 const float rsv = (MODE == 0) ? 1.0f : rsvv[ai][m];
;                 f32x4 v[2][2];
; #pragma unroll
;                 for (int bj = 0; bj < 2; ++bj)
; #pragma unroll
;                     for (int n = 0; n < 2; ++n) v[bj][n] = acc[ai][bj][m][n] * rsv;
;                 if (type < 2) {
;                     float ss = 0.f;
; #pragma unroll
;                     for (int bj = 0; bj < 2; ++bj)
; #pragma unroll
;                         for (int n = 0; n < 2; ++n) { const f32x4 x = v[bj][n]; ss += (x[0] * x[0] + x[1] * x[1]) + (x[2] * x[2] + x[3] * x[3]); }
;                     ss = sum_x16(ss); ss = sum_x32(ss);
;                     const float inv = __builtin_amdgcn_rsqf(ss * (1.0f / 64.0f) + RMS_EPS);
; #pragma unroll
;                     for (int bj = 0; bj < 2; ++bj)
; #pragma unroll
;                         for (int n = 0; n < 2; ++n) v[bj][n] = v[bj][n] * gv[bj][n] * inv;
;                 }
;                 bf16_t* p = p0 + (size_t)(8 * ai + m) * step16;
; #pragma unroll
;                 for (int bj = 0; bj < 2; ++bj) { u32x4 w; w.x = cvt_pk_bf16(v[bj][0][0], v[bj][0][1]); w.y = cvt_pk_bf16(v[bj][0][2], v[bj][0][3]); w.z = cvt_pk_bf16(v[bj][1][0], v[bj][1][1]); w.w = cvt_pk_bf16(v[bj][1][2], v[bj][1][3]);
;                     st16_wt(p + 32 * bj, w); }
;     ...
; #pragma unroll
;         for (int a = 0; a < 2; ++a)
; #pragma unroll
;             for (int b = 0; b < 2; ++b)
; #pragma unroll
;                 for (int m = 0; m < 4; ++m)
; #pragma unroll
;                     for (int n = 0; n < 2; ++n) PG8_ZERO4(acc[a][b][m][n]);
.LBB0_573:
	v_lshl_add_u64 v[32:33], v[48:49], 0, s[12:13]
	v_mov_b32_e32 v254, v32
	v_mov_b32_e32 v255, v33
	s_mov_b32 s100, s12
	v_cvt_pk_bf16_f32 v228, v52, v53
	v_cvt_pk_bf16_f32 v229, v38, v39
	v_cvt_pk_bf16_f32 v230, v54, v55
	v_cvt_pk_bf16_f32 v231, v50, v51
	v_cvt_pk_bf16_f32 v232, v44, v45
	v_cvt_pk_bf16_f32 v233, v34, v35
	v_cvt_pk_bf16_f32 v234, v40, v41
	v_cvt_pk_bf16_f32 v235, v36, v37
	v_pk_mul_f32 v[22:23], v[22:23], v[148:149] op_sel_hi:[1,0]
	v_pk_mul_f32 v[36:37], v[20:21], v[148:149] op_sel_hi:[1,0]
	v_pk_mul_f32 v[34:35], v[18:19], v[148:149] op_sel_hi:[1,0]
	v_pk_mul_f32 v[38:39], v[16:17], v[148:149] op_sel_hi:[1,0]
	v_pk_mul_f32 v[18:19], v[30:31], v[148:149] op_sel_hi:[1,0]
	v_pk_mul_f32 v[28:29], v[28:29], v[148:149] op_sel_hi:[1,0]
	v_pk_mul_f32 v[20:21], v[26:27], v[148:149] op_sel_hi:[1,0]
	s_and_b64 vcc, exec, s[38:39]
	v_pk_mul_f32 v[24:25], v[24:25], v[148:149] op_sel_hi:[1,0]
	s_cbranch_vccnz .LBB0_575
	v_pk_mul_f32 v[16:17], v[18:19], v[18:19]
	v_pk_fma_f32 v[16:17], v[20:21], v[20:21], v[16:17]
	v_pk_fma_f32 v[16:17], v[22:23], v[22:23], v[16:17]
	v_pk_fma_f32 v[16:17], v[24:25], v[24:25], v[16:17]
	v_pk_fma_f32 v[16:17], v[28:29], v[28:29], v[16:17]
	v_pk_fma_f32 v[16:17], v[34:35], v[34:35], v[16:17]
	v_pk_fma_f32 v[16:17], v[36:37], v[36:37], v[16:17]
	v_pk_fma_f32 v[16:17], v[38:39], v[38:39], v[16:17]
	v_add_f32_e32 v16, v16, v17
	v_mov_b32_e32 v17, v16
	s_nop 1
	v_permlane16_swap_b32_e32 v16, v17
	v_add_f32_e32 v16, v16, v17
	v_mov_b32_e32 v17, v16
	s_nop 1
	v_permlane32_swap_b32_e32 v16, v17
	v_add_f32_e32 v16, v16, v17
	v_fmamk_f32 v16, v16, 0x3c800000, v201
	v_rsq_f32_e32 v16, v16
	s_waitcnt lgkmcnt(0)
	v_pk_mul_f32 v[26:27], v[124:125], v[36:37]
	v_pk_mul_f32 v[22:23], v[126:127], v[22:23]
	v_pk_mul_f32 v[30:31], v[120:121], v[38:39]
	v_pk_mul_f32 v[36:37], v[26:27], v[16:17] op_sel_hi:[1,0]
	v_pk_mul_f32 v[26:27], v[122:123], v[34:35]
	v_pk_mul_f32 v[18:19], v[118:119], v[18:19]
	v_pk_mul_f32 v[34:35], v[26:27], v[16:17] op_sel_hi:[1,0]
	v_pk_mul_f32 v[26:27], v[116:117], v[28:29]
	v_pk_mul_f32 v[20:21], v[114:115], v[20:21]
	v_pk_mul_f32 v[24:25], v[112:113], v[24:25]
	v_pk_mul_f32 v[22:23], v[22:23], v[16:17] op_sel_hi:[1,0]
	v_pk_mul_f32 v[38:39], v[30:31], v[16:17] op_sel_hi:[1,0]
	v_pk_mul_f32 v[18:19], v[18:19], v[16:17] op_sel_hi:[1,0]
	v_pk_mul_f32 v[28:29], v[26:27], v[16:17] op_sel_hi:[1,0]
	v_pk_mul_f32 v[20:21], v[20:21], v[16:17] op_sel_hi:[1,0]
	v_pk_mul_f32 v[24:25], v[24:25], v[16:17] op_sel_hi:[1,0]
.LBB0_575:
	v_lshl_add_u64 v[16:17], v[32:33], 0, s[12:13]
	v_cvt_pk_bf16_f32 v236, v36, v37
	v_cvt_pk_bf16_f32 v237, v22, v23
	v_cvt_pk_bf16_f32 v238, v38, v39
	v_cvt_pk_bf16_f32 v239, v34, v35
	v_cvt_pk_bf16_f32 v240, v28, v29
	v_cvt_pk_bf16_f32 v241, v18, v19
	v_cvt_pk_bf16_f32 v242, v24, v25
	v_cvt_pk_bf16_f32 v243, v20, v21
	v_pk_mul_f32 v[6:7], v[6:7], v[144:145] op_sel_hi:[1,0]
	v_pk_mul_f32 v[18:19], v[4:5], v[144:145] op_sel_hi:[1,0]
	v_pk_mul_f32 v[4:5], v[2:3], v[144:145] op_sel_hi:[1,0]
	v_pk_mul_f32 v[20:21], v[0:1], v[144:145] op_sel_hi:[1,0]
	v_pk_mul_f32 v[0:1], v[14:15], v[144:145] op_sel_hi:[1,0]
	v_pk_mul_f32 v[12:13], v[12:13], v[144:145] op_sel_hi:[1,0]
	v_pk_mul_f32 v[2:3], v[10:11], v[144:145] op_sel_hi:[1,0]
	s_and_b64 vcc, exec, s[38:39]
	v_pk_mul_f32 v[8:9], v[8:9], v[144:145] op_sel_hi:[1,0]
	s_cbranch_vccnz .LBB0_577
	v_pk_mul_f32 v[10:11], v[0:1], v[0:1]
	v_pk_fma_f32 v[10:11], v[2:3], v[2:3], v[10:11]
	v_pk_fma_f32 v[10:11], v[4:5], v[4:5], v[10:11]
	v_pk_fma_f32 v[10:11], v[6:7], v[6:7], v[10:11]
	v_pk_fma_f32 v[10:11], v[8:9], v[8:9], v[10:11]
	v_pk_fma_f32 v[10:11], v[12:13], v[12:13], v[10:11]
	v_pk_fma_f32 v[10:11], v[18:19], v[18:19], v[10:11]
	v_pk_fma_f32 v[10:11], v[20:21], v[20:21], v[10:11]
	v_add_f32_e32 v10, v10, v11
	v_mov_b32_e32 v11, v10
	s_nop 1
	v_permlane16_swap_b32_e32 v10, v11
	v_add_f32_e32 v10, v10, v11
	v_mov_b32_e32 v11, v10
	s_nop 1
	v_permlane32_swap_b32_e32 v10, v11
	v_add_f32_e32 v10, v10, v11
	v_fmamk_f32 v10, v10, 0x3c800000, v201
	v_rsq_f32_e32 v10, v10
	s_waitcnt lgkmcnt(0)
	v_pk_mul_f32 v[14:15], v[124:125], v[18:19]
	v_pk_mul_f32 v[6:7], v[126:127], v[6:7]
	v_pk_mul_f32 v[4:5], v[122:123], v[4:5]
	v_pk_mul_f32 v[18:19], v[14:15], v[10:11] op_sel_hi:[1,0]
	v_pk_mul_f32 v[14:15], v[120:121], v[20:21]
	v_pk_mul_f32 v[0:1], v[118:119], v[0:1]
	v_pk_mul_f32 v[12:13], v[116:117], v[12:13]
	v_pk_mul_f32 v[2:3], v[114:115], v[2:3]
	v_pk_mul_f32 v[8:9], v[112:113], v[8:9]
	v_pk_mul_f32 v[6:7], v[6:7], v[10:11] op_sel_hi:[1,0]
	v_pk_mul_f32 v[4:5], v[4:5], v[10:11] op_sel_hi:[1,0]
	v_pk_mul_f32 v[20:21], v[14:15], v[10:11] op_sel_hi:[1,0]
	v_pk_mul_f32 v[0:1], v[0:1], v[10:11] op_sel_hi:[1,0]
	v_pk_mul_f32 v[12:13], v[12:13], v[10:11] op_sel_hi:[1,0]
	v_pk_mul_f32 v[2:3], v[2:3], v[10:11] op_sel_hi:[1,0]
	v_pk_mul_f32 v[8:9], v[8:9], v[10:11] op_sel_hi:[1,0]
.LBB0_577:
	v_lshl_add_u64 v[10:11], v[16:17], 0, s[12:13]
	v_cvt_pk_bf16_f32 v244, v18, v19
	v_cvt_pk_bf16_f32 v245, v6, v7
	v_cvt_pk_bf16_f32 v246, v20, v21
	v_cvt_pk_bf16_f32 v247, v4, v5
	v_cvt_pk_bf16_f32 v248, v12, v13
	v_cvt_pk_bf16_f32 v249, v0, v1
	v_cvt_pk_bf16_f32 v250, v8, v9
	v_cvt_pk_bf16_f32 v251, v2, v3
	s_andn2_b64 vcc, exec, s[36:37]
	s_mov_b64 s[22:23], -1
	s_mov_b32 s101, 6
	s_cbranch_vccnz .LBB0_524
	s_andn2_b64 vcc, exec, s[8:9]
	v_mov_b64 v[132:133], 0
	v_mov_b64 v[134:135], 0
	v_mov_b64 v[128:129], 0
	v_mov_b64 v[130:131], 0
	v_mov_b64 v[100:101], 0
	v_mov_b64 v[102:103], 0
	v_mov_b64 v[96:97], 0
	v_mov_b64 v[98:99], 0
	v_mov_b64 v[84:85], 0
	v_mov_b64 v[86:87], 0
	v_mov_b64 v[80:81], 0
	v_mov_b64 v[82:83], 0
	v_mov_b64 v[68:69], 0
	v_mov_b64 v[70:71], 0
	v_mov_b64 v[64:65], 0
	v_mov_b64 v[66:67], 0
	v_mov_b64 v[140:141], 0
	v_mov_b64 v[142:143], 0
	v_mov_b64 v[136:137], 0
	v_mov_b64 v[138:139], 0
	v_mov_b64 v[108:109], 0
	v_mov_b64 v[110:111], 0
	v_mov_b64 v[104:105], 0
	v_mov_b64 v[106:107], 0
	v_mov_b64 v[92:93], 0
	v_mov_b64 v[94:95], 0
	v_mov_b64 v[88:89], 0
	v_mov_b64 v[90:91], 0
	v_mov_b64 v[76:77], 0
	v_mov_b64 v[78:79], 0
	v_mov_b64 v[72:73], 0
	v_mov_b64 v[74:75], 0
	v_mov_b64 v[52:53], 0
	v_mov_b64 v[54:55], 0
	v_mov_b64 v[48:49], 0
	v_mov_b64 v[50:51], 0
	v_mov_b64 v[36:37], 0
	v_mov_b64 v[38:39], 0
	v_mov_b64 v[32:33], 0
	v_mov_b64 v[34:35], 0
	v_mov_b64 v[20:21], 0
	v_mov_b64 v[22:23], 0
	v_mov_b64 v[16:17], 0
	v_mov_b64 v[18:19], 0
	v_mov_b64 v[4:5], 0
	v_mov_b64 v[6:7], 0
	v_mov_b64 v[0:1], 0
	v_mov_b64 v[2:3], 0
	v_mov_b64 v[60:61], 0
	v_mov_b64 v[62:63], 0
	v_mov_b64 v[56:57], 0
	v_mov_b64 v[58:59], 0
	v_mov_b64 v[44:45], 0
	v_mov_b64 v[46:47], 0
	v_mov_b64 v[40:41], 0
	v_mov_b64 v[42:43], 0
	v_mov_b64 v[28:29], 0
	v_mov_b64 v[30:31], 0
	v_mov_b64 v[24:25], 0
	v_mov_b64 v[26:27], 0
	v_mov_b64 v[12:13], 0
	v_mov_b64 v[14:15], 0
	v_mov_b64 v[8:9], 0
	v_mov_b64 v[10:11], 0
	s_cbranch_vccnz .LBB0_523
	s_barrier
	s_branch .LBB0_523
